# v45 + lru_conv_own prompt-row loads de-serialised (rows 1..13 issued together after row 0)
# baseline (speedup 1.0000x reference)
; __device__ __forceinline__ void unpack8(const v4u w, float (&f)[8]) { f[0] = bf_lo(w.x); f[1] = bf_hi(w.x); f[2] = bf_lo(w.y); f[3] = bf_hi(w.y); f[4] = bf_lo(w.z); f[5] = bf_hi(w.z); f[6] = bf_lo(w.w); f[7] = bf_hi(w.w); }
; __device__ __forceinline__ v4u pack8(const float (&f)[8]) { v4u w; w.x = cvt_pk_bf16(f[0], f[1]); w.y = cvt_pk_bf16(f[2], f[3]); w.z = cvt_pk_bf16(f[4], f[5]); w.w = cvt_pk_bf16(f[6], f[7]); return w; }
; __device__ __forceinline__ void lru_conv_own(const Frame& F, CArgs* A, int j, const bf16* U, bf16* UC) {
;     ...
;         const int pm = P >> 3, hd = P & 7, c = hd * 256 + (F.tid & 31) * 8, m0 = pm * 256 + (F.tid >> 5) * 16, t0 = m0 & 4095;
;         float w[4][8], bias[8], x3[8], x2[8], x1[8];
; #pragma unroll
;         for (int k = 0; k < 4; ++k) load8f(cw + (size_t)k * 2048 + c, w[k]);
;         load8f(cb + c, bias);
;         if (t0 != 0) { unpack8(*(const v4u*)(U + (size_t)(m0 - 3) * 2048 + c), x3); unpack8(*(const v4u*)(U + (size_t)(m0 - 2) * 2048 + c), x2); unpack8(*(const v4u*)(U + (size_t)(m0 - 1) * 2048 + c), x1); }
;         else {
; #pragma unroll
;             for (int e = 0; e < 8; ++e) { x3[e] = 0.f; x2[e] = 0.f; x1[e] = 0.f; } }
; #pragma unroll
;         for (int r = 0; r < 16; ++r) { float x0[8], o[8]; unpack8(*(const v4u*)(U + (size_t)(m0 + r) * 2048 + c), x0);
; #pragma unroll
;             for (int e = 0; e < 8; ++e) o[e] = bias[e] + w[0][e] * x3[e] + w[1][e] * x2[e] + w[2][e] * x1[e] + w[3][e] * x0[e];
;             *(v4u*)(UC + (size_t)(m0 + r) * 2048 + c) = pack8(o);
.LBB0_279:
	s_or_b64 exec, exec, s[2:3]
	v_mov_b32_e32 v45, v1
	s_waitcnt vmcnt(10)
	v_lshl_add_u64 v[50:51], s[18:19], 0, v[44:45]
	v_lshlrev_b64 v[86:87], 12, v[42:43]
	v_lshl_add_u64 v[48:49], v[50:51], 0, v[86:87]
	global_load_dwordx4 v[52:55], v[48:49], off
	s_mov_b64 s[16:17], 0x1000
	v_lshl_add_u64 v[198:199], v[48:49], 0, s[16:17]
	global_load_dwordx4 v[128:131], v[198:199], off
	s_mov_b64 s[16:17], 0x2000
	v_lshl_add_u64 v[196:197], v[48:49], 0, s[16:17]
	global_load_dwordx4 v[132:135], v[196:197], off
	s_mov_b64 s[16:17], 0x3000
	v_lshl_add_u64 v[198:199], v[48:49], 0, s[16:17]
	global_load_dwordx4 v[136:139], v[198:199], off
	s_mov_b64 s[16:17], 0x4000
	v_lshl_add_u64 v[196:197], v[48:49], 0, s[16:17]
	global_load_dwordx4 v[140:143], v[196:197], off
	s_mov_b64 s[16:17], 0x5000
	v_lshl_add_u64 v[198:199], v[48:49], 0, s[16:17]
	global_load_dwordx4 v[144:147], v[198:199], off
	s_mov_b64 s[16:17], 0x6000
	v_lshl_add_u64 v[196:197], v[48:49], 0, s[16:17]
	global_load_dwordx4 v[148:151], v[196:197], off
	s_mov_b64 s[16:17], 0x7000
	v_lshl_add_u64 v[198:199], v[48:49], 0, s[16:17]
	global_load_dwordx4 v[152:155], v[198:199], off
	s_mov_b64 s[16:17], 0x8000
	v_lshl_add_u64 v[196:197], v[48:49], 0, s[16:17]
	global_load_dwordx4 v[156:159], v[196:197], off
	s_mov_b64 s[16:17], 0x9000
	v_lshl_add_u64 v[198:199], v[48:49], 0, s[16:17]
	global_load_dwordx4 v[160:163], v[198:199], off
	s_mov_b64 s[16:17], 0xa000
	v_lshl_add_u64 v[196:197], v[48:49], 0, s[16:17]
	global_load_dwordx4 v[164:167], v[196:197], off
	s_mov_b64 s[16:17], 0xb000
	v_lshl_add_u64 v[198:199], v[48:49], 0, s[16:17]
	global_load_dwordx4 v[170:173], v[198:199], off
	s_mov_b64 s[16:17], 0xc000
	v_lshl_add_u64 v[196:197], v[48:49], 0, s[16:17]
	global_load_dwordx4 v[176:179], v[196:197], off
	s_mov_b64 s[16:17], 0xd000
	v_lshl_add_u64 v[198:199], v[48:49], 0, s[16:17]
	global_load_dwordx4 v[190:193], v[198:199], off
	s_waitcnt vmcnt(23)
	v_mov_b32_e32 v56, v28
	s_waitcnt vmcnt(20)
	v_mov_b32_e32 v57, v12
	v_mov_b32_e32 v62, v107
	v_mov_b32_e32 v60, v109
	v_mov_b32_e32 v80, v103
	v_mov_b32_e32 v78, v105
	v_mov_b32_e32 v84, v99
	v_mov_b32_e32 v82, v101
	v_mov_b32_e32 v76, v91
	v_mov_b32_e32 v90, v95
	v_mov_b32_e32 v92, v97
	v_mov_b32_e32 v74, v93
	v_lshl_add_u64 v[46:47], s[46:47], 0, v[44:45]
	v_lshl_add_u64 v[86:87], v[46:47], 0, v[86:87]
	v_ashrrev_i32_e32 v44, 12, v42
	v_add_u32_e32 v44, s67, v44
	v_mul_i32_i24_e32 v44, 3, v44
	s_movk_i32 s2, 0xff0
	v_ashrrev_i32_e32 v45, 31, v44
	v_cmp_eq_u32_e32 vcc, s2, v111
	s_waitcnt vmcnt(13)
	v_lshlrev_b32_e32 v65, 16, v52
	v_and_b32_e32 v59, 0xffff0000, v52
	v_lshlrev_b32_e32 v69, 16, v53
	v_and_b32_e32 v67, 0xffff0000, v53
	v_mov_b32_e32 v52, v34
	v_mov_b32_e32 v53, v22
	v_pk_mul_f32 v[48:49], v[52:53], v[106:107]
	v_lshlrev_b32_e32 v73, 16, v54
	v_add_f32_e32 v22, v18, v48
	v_add_f32_e32 v58, v22, v49
	v_mov_b32_e32 v22, v35
	v_pk_mul_f32 v[34:35], v[22:23], v[108:109]
	v_mov_b32_e32 v49, v6
	v_add_f32_e32 v6, v19, v34
	v_mov_b32_e32 v48, v38
	v_add_f32_e32 v106, v6, v35
	v_mov_b32_e32 v6, v39
	v_mov_b32_e32 v38, v36
	v_mov_b32_e32 v39, v24
	v_pk_mul_f32 v[34:35], v[38:39], v[102:103]
	v_and_b32_e32 v71, 0xffff0000, v54
	v_add_f32_e32 v24, v20, v34
	v_add_f32_e32 v66, v24, v35
	v_mov_b32_e32 v24, v37
	v_pk_mul_f32 v[36:37], v[24:25], v[104:105]
	v_mov_b32_e32 v35, v8
	v_add_f32_e32 v8, v21, v36
	v_mov_b32_e32 v34, v40
	v_add_f32_e32 v64, v8, v37
	v_mov_b32_e32 v8, v41
	v_mov_b32_e32 v40, v26
	v_mov_b32_e32 v41, v10
	v_pk_mul_f32 v[36:37], v[40:41], v[98:99]
	v_lshlrev_b32_e32 v77, 16, v55
	v_add_f32_e32 v10, v14, v36
	v_add_f32_e32 v68, v10, v37
	v_mov_b32_e32 v10, v27
	v_pk_mul_f32 v[26:27], v[10:11], v[100:101]
	v_mov_b32_e32 v37, v2
	v_add_f32_e32 v2, v15, v26
	v_add_f32_e32 v102, v2, v27
	v_pk_mul_f32 v[26:27], v[56:57], v[94:95]
	v_and_b32_e32 v75, 0xffff0000, v55
	v_add_f32_e32 v12, v16, v26
	v_add_f32_e32 v70, v12, v27
	v_mov_b32_e32 v12, v29
	v_pk_mul_f32 v[28:29], v[52:53], v[62:63]
	v_mov_b32_e32 v54, v32
	v_add_f32_e32 v28, v18, v28
	v_add_f32_e32 v100, v28, v29
	v_pk_mul_f32 v[28:29], v[22:23], v[60:61]
	v_mov_b32_e32 v55, v4
	v_add_f32_e32 v28, v19, v28
	v_add_f32_e32 v43, v28, v29
	v_pk_mul_f32 v[28:29], v[38:39], v[80:81]
	v_pk_mul_f32 v[26:27], v[12:13], v[96:97]
	v_add_f32_e32 v28, v20, v28
	v_add_f32_e32 v80, v28, v29
	v_pk_mul_f32 v[28:29], v[24:25], v[78:79]
	v_pk_mul_f32 v[98:99], v[54:55], v[76:77]
	v_add_f32_e32 v28, v21, v28
	v_add_f32_e32 v78, v28, v29
	v_pk_mul_f32 v[28:29], v[40:41], v[84:85]
	v_add_f32_e32 v4, v17, v26
	v_add_f32_e32 v28, v14, v28
	v_add_f32_e32 v84, v28, v29
	v_pk_mul_f32 v[28:29], v[10:11], v[82:83]
	v_add_f32_e32 v60, v70, v98
	v_add_f32_e32 v28, v15, v28
	v_add_f32_e32 v82, v28, v29
	v_pk_mul_f32 v[28:29], v[56:57], v[90:91]
	v_add_f32_e32 v72, v4, v27
	v_mov_b32_e32 v4, v33
	v_add_f32_e32 v28, v16, v28
	v_add_f32_e32 v91, v60, v99
	v_pk_mul_f32 v[98:99], v[56:57], v[76:77]
	v_add_f32_e32 v94, v28, v29
	v_pk_mul_f32 v[28:29], v[12:13], v[92:93]
	v_add_f32_e32 v60, v16, v98
	v_pk_mul_f32 v[92:93], v[4:5], v[74:75]
	v_add_f32_e32 v76, v60, v99
	v_add_f32_e32 v60, v72, v92
	v_add_f32_e32 v95, v60, v93
	v_pk_mul_f32 v[92:93], v[12:13], v[74:75]
	v_mov_b32_e32 v36, v30
	v_add_f32_e32 v60, v17, v92
	v_mov_b32_e32 v72, v85
	v_add_f32_e32 v74, v60, v93
	v_pk_mul_f32 v[92:93], v[36:37], v[72:73]
	v_mov_b32_e32 v2, v31
	v_add_f32_e32 v60, v68, v92
	v_add_f32_e32 v85, v60, v93
	v_pk_mul_f32 v[92:93], v[40:41], v[72:73]
	v_mov_b32_e32 v70, v83
	v_add_f32_e32 v60, v14, v92
	v_add_f32_e32 v72, v60, v93
	v_pk_mul_f32 v[92:93], v[2:3], v[70:71]
	v_mov_b32_e32 v68, v81
	v_add_f32_e32 v60, v102, v92
; __device__ __forceinline__ void unpack8(const v4u w, float (&f)[8]) { f[0] = bf_lo(w.x); f[1] = bf_hi(w.x); f[2] = bf_lo(w.y); f[3] = bf_hi(w.y); f[4] = bf_lo(w.z); f[5] = bf_hi(w.z); f[6] = bf_lo(w.w); f[7] = bf_hi(w.w); }
; __device__ __forceinline__ v4u pack8(const float (&f)[8]) { v4u w; w.x = cvt_pk_bf16(f[0], f[1]); w.y = cvt_pk_bf16(f[2], f[3]); w.z = cvt_pk_bf16(f[4], f[5]); w.w = cvt_pk_bf16(f[6], f[7]); return w; }
; __device__ __forceinline__ void lru_conv_own(const Frame& F, CArgs* A, int j, const bf16* U, bf16* UC) {
;     ...
;         for (int r = 0; r < 16; ++r) { float x0[8], o[8]; unpack8(*(const v4u*)(U + (size_t)(m0 + r) * 2048 + c), x0);
; #pragma unroll
;             for (int e = 0; e < 8; ++e) o[e] = bias[e] + w[0][e] * x3[e] + w[1][e] * x2[e] + w[2][e] * x1[e] + w[3][e] * x0[e];
;             *(v4u*)(UC + (size_t)(m0 + r) * 2048 + c) = pack8(o);
;             if (t0 + r >= TSEQ - 3) store8f(A->out + O_LCP + ((size_t)(j * 2 + (m0 >> 12)) * 3 + (t0 + r - (TSEQ - 3))) * 2048 + c, x0);
; #pragma unroll
;             for (int e = 0; e < 8; ++e) { x3[e] = x2[e]; x2[e] = x1[e]; x1[e] = x0[e]; } }
	v_add_f32_e32 v83, v60, v93
	v_pk_mul_f32 v[92:93], v[10:11], v[70:71]
	v_or_b32_e32 v26, 1, v42
	v_add_f32_e32 v60, v15, v92
	v_add_f32_e32 v70, v60, v93
	v_pk_mul_f32 v[92:93], v[34:35], v[68:69]
	v_ashrrev_i32_e32 v27, 31, v26
	v_add_f32_e32 v60, v66, v92
	v_add_f32_e32 v81, v60, v93
	v_pk_mul_f32 v[92:93], v[38:39], v[68:69]
	v_mov_b32_e32 v66, v79
	v_add_f32_e32 v60, v20, v92
	v_add_f32_e32 v68, v60, v93
	v_pk_mul_f32 v[92:93], v[8:9], v[66:67]
	v_lshlrev_b64 v[26:27], 12, v[26:27]
	v_add_f32_e32 v60, v64, v92
	v_mov_b32_e32 v64, v63
	v_pk_mul_f32 v[62:63], v[48:49], v[64:65]
	v_add_f32_e32 v79, v60, v93
	v_pk_mul_f32 v[92:93], v[24:25], v[66:67]
	v_add_f32_e32 v58, v58, v62
	v_add_f32_e32 v60, v21, v92
	v_add_f32_e32 v92, v58, v63
	v_pk_mul_f32 v[62:63], v[52:53], v[64:65]
	v_add_f32_e32 v113, v60, v93
	v_add_f32_e32 v58, v18, v62
	v_add_f32_e32 v66, v58, v63
	v_mov_b32_e32 v58, v61
	v_pk_mul_f32 v[60:61], v[6:7], v[58:59]
	v_lshl_add_u64 v[88:89], v[50:51], 0, v[26:27]
	v_add_f32_e32 v60, v106, v60
	v_add_f32_e32 v62, v60, v61
	v_pk_mul_f32 v[60:61], v[22:23], v[58:59]
	v_mov_b32_e32 v98, v77
	v_add_f32_e32 v58, v19, v60
	v_add_f32_e32 v64, v58, v61
	v_cvt_pk_bf16_f32 v60, v92, v62
	v_cvt_pk_bf16_f32 v61, v81, v79
	v_cvt_pk_bf16_f32 v62, v85, v83
	v_cvt_pk_bf16_f32 v63, v91, v95
	s_nop 0
	v_add_f32_e32 v28, v17, v28
	global_store_dwordx4 v[86:87], v[60:63], off
	v_add_f32_e32 v90, v28, v29
	v_mov_b32_e32 v92, v73
	v_mov_b32_e32 v88, v71
	v_lshl_add_u64 v[30:31], v[46:47], 0, v[26:27]
	v_or_b32_e32 v26, 2, v42
	v_ashrrev_i32_e32 v27, 31, v26
	v_lshlrev_b64 v[26:27], 12, v[26:27]
	v_lshl_add_u64 v[32:33], v[50:51], 0, v[26:27]
	v_or_b32_e32 v28, 3, v42
	v_ashrrev_i32_e32 v29, 31, v28
	v_lshlrev_b64 v[96:97], 12, v[28:29]
	v_lshl_add_u64 v[28:29], v[50:51], 0, v[96:97]
	v_lshl_add_u64 v[60:61], v[46:47], 0, v[96:97]
	v_or_b32_e32 v62, 4, v42
	v_ashrrev_i32_e32 v63, 31, v62
	v_lshl_add_u64 v[26:27], v[46:47], 0, v[26:27]
	s_waitcnt vmcnt(14)
	s_waitcnt vmcnt(13)
	v_lshlrev_b32_e32 v99, 16, v131
	v_pk_mul_f32 v[86:87], v[54:55], v[98:99]
	v_and_b32_e32 v95, 0xffff0000, v131
	v_add_f32_e32 v58, v94, v86
	v_add_f32_e32 v77, v58, v87
	v_pk_mul_f32 v[86:87], v[56:57], v[98:99]
	v_mov_b32_e32 v94, v75
	v_add_f32_e32 v58, v16, v86
	v_add_f32_e32 v107, v58, v87
	v_pk_mul_f32 v[86:87], v[4:5], v[94:95]
	v_lshlrev_b32_e32 v93, 16, v130
	v_add_f32_e32 v58, v90, v86
	v_add_f32_e32 v75, v58, v87
	v_pk_mul_f32 v[86:87], v[12:13], v[94:95]
	v_and_b32_e32 v89, 0xffff0000, v130
	v_add_f32_e32 v58, v17, v86
	v_add_f32_e32 v108, v58, v87
	v_pk_mul_f32 v[86:87], v[40:41], v[92:93]
	v_pk_mul_f32 v[90:91], v[36:37], v[92:93]
	v_add_f32_e32 v58, v14, v86
	v_add_f32_e32 v104, v58, v87
	v_pk_mul_f32 v[86:87], v[10:11], v[88:89]
	v_lshlrev_b32_e32 v85, 16, v129
	v_add_f32_e32 v73, v84, v90
	v_add_f32_e32 v58, v15, v86
	v_mov_b32_e32 v84, v69
	v_add_f32_e32 v73, v73, v91
	v_pk_mul_f32 v[90:91], v[2:3], v[88:89]
	v_add_f32_e32 v105, v58, v87
	v_pk_mul_f32 v[86:87], v[38:39], v[84:85]
	v_and_b32_e32 v83, 0xffff0000, v129
	v_add_f32_e32 v71, v82, v90
	v_add_f32_e32 v58, v20, v86
	v_mov_b32_e32 v82, v67
	v_add_f32_e32 v71, v71, v91
	v_pk_mul_f32 v[90:91], v[34:35], v[84:85]
	v_add_f32_e32 v106, v58, v87
	v_pk_mul_f32 v[86:87], v[24:25], v[82:83]
	v_lshlrev_b32_e32 v81, 16, v128
	v_add_f32_e32 v69, v80, v90
	v_add_f32_e32 v58, v21, v86
	v_mov_b32_e32 v80, v65
	v_add_f32_e32 v69, v69, v91
	v_pk_mul_f32 v[90:91], v[8:9], v[82:83]
	v_add_f32_e32 v112, v58, v87
	v_pk_mul_f32 v[86:87], v[52:53], v[80:81]
	v_and_b32_e32 v79, 0xffff0000, v128
	v_add_f32_e32 v67, v78, v90
	v_add_f32_e32 v58, v18, v86
	v_mov_b32_e32 v78, v59
	v_add_f32_e32 v67, v67, v91
	v_pk_mul_f32 v[90:91], v[48:49], v[80:81]
	v_add_f32_e32 v109, v58, v87
	v_pk_mul_f32 v[86:87], v[6:7], v[78:79]
	v_add_f32_e32 v65, v100, v90
	v_add_f32_e32 v43, v43, v86
	v_add_f32_e32 v65, v65, v91
	v_add_f32_e32 v43, v43, v87
	v_cvt_pk_bf16_f32 v120, v65, v43
	v_cvt_pk_bf16_f32 v121, v69, v67
	v_cvt_pk_bf16_f32 v122, v73, v71
	v_cvt_pk_bf16_f32 v123, v77, v75
	s_nop 0
	v_mov_b32_e32 v100, v99
	v_mov_b32_e32 v96, v95
	v_pk_mul_f32 v[58:59], v[22:23], v[78:79]
	v_mov_b32_e32 v90, v93
	v_mov_b32_e32 v86, v89
	v_lshlrev_b64 v[102:103], 12, v[62:63]
	v_lshl_add_u64 v[62:63], v[50:51], 0, v[102:103]
	global_store_dwordx4 v[30:31], v[120:123], off
	v_lshl_add_u64 v[30:31], v[46:47], 0, v[102:103]
	v_add_f32_e32 v58, v19, v58
	v_add_f32_e32 v92, v58, v59
	v_or_b32_e32 v32, 5, v42
	v_ashrrev_i32_e32 v33, 31, v32
	v_lshlrev_b64 v[58:59], 12, v[32:33]
	v_lshl_add_u64 v[32:33], v[50:51], 0, v[58:59]
	s_nop 0
	s_waitcnt vmcnt(13)
; __device__ __forceinline__ void unpack8(const v4u w, float (&f)[8]) { f[0] = bf_lo(w.x); f[1] = bf_hi(w.x); f[2] = bf_lo(w.y); f[3] = bf_hi(w.y); f[4] = bf_lo(w.z); f[5] = bf_hi(w.z); f[6] = bf_lo(w.w); f[7] = bf_hi(w.w); }
; __device__ __forceinline__ v4u pack8(const float (&f)[8]) { v4u w; w.x = cvt_pk_bf16(f[0], f[1]); w.y = cvt_pk_bf16(f[2], f[3]); w.z = cvt_pk_bf16(f[4], f[5]); w.w = cvt_pk_bf16(f[6], f[7]); return w; }
; __device__ __forceinline__ void lru_conv_own(const Frame& F, CArgs* A, int j, const bf16* U, bf16* UC) {
;     ...
;         for (int r = 0; r < 16; ++r) { float x0[8], o[8]; unpack8(*(const v4u*)(U + (size_t)(m0 + r) * 2048 + c), x0);
; #pragma unroll
;             for (int e = 0; e < 8; ++e) o[e] = bias[e] + w[0][e] * x3[e] + w[1][e] * x2[e] + w[2][e] * x1[e] + w[3][e] * x0[e];
;             *(v4u*)(UC + (size_t)(m0 + r) * 2048 + c) = pack8(o);
;             if (t0 + r >= TSEQ - 3) store8f(A->out + O_LCP + ((size_t)(j * 2 + (m0 >> 12)) * 3 + (t0 + r - (TSEQ - 3))) * 2048 + c, x0);
; #pragma unroll
;             for (int e = 0; e < 8; ++e) { x3[e] = x2[e]; x2[e] = x1[e]; x1[e] = x0[e]; } }
	v_lshlrev_b32_e32 v101, 16, v135
	v_pk_mul_f32 v[98:99], v[54:55], v[100:101]
	v_and_b32_e32 v97, 0xffff0000, v135
	v_add_f32_e32 v43, v76, v98
	v_add_f32_e32 v65, v43, v99
	v_pk_mul_f32 v[98:99], v[56:57], v[100:101]
	v_pk_mul_f32 v[94:95], v[4:5], v[96:97]
	v_add_f32_e32 v43, v16, v98
	v_add_f32_e32 v80, v43, v99
	v_add_f32_e32 v43, v74, v94
	v_pk_mul_f32 v[74:75], v[12:13], v[96:97]
	v_lshlrev_b32_e32 v91, 16, v134
	v_add_f32_e32 v78, v43, v95
	v_add_f32_e32 v43, v17, v74
	v_add_f32_e32 v84, v43, v75
	v_pk_mul_f32 v[74:75], v[40:41], v[90:91]
	v_and_b32_e32 v87, 0xffff0000, v134
	v_add_f32_e32 v43, v14, v74
	v_pk_mul_f32 v[94:95], v[36:37], v[90:91]
	v_add_f32_e32 v43, v43, v75
	v_add_f32_e32 v71, v72, v94
	v_pk_mul_f32 v[74:75], v[10:11], v[86:87]
	v_pk_mul_f32 v[88:89], v[2:3], v[86:87]
	v_lshlrev_b32_e32 v77, 16, v133
	v_add_f32_e32 v82, v71, v95
	v_add_f32_e32 v71, v15, v74
	v_add_f32_e32 v70, v70, v88
	v_mov_b32_e32 v76, v85
	v_add_f32_e32 v88, v70, v89
	v_add_f32_e32 v86, v71, v75
	v_pk_mul_f32 v[70:71], v[38:39], v[76:77]
	v_and_b32_e32 v73, 0xffff0000, v133
	v_add_f32_e32 v70, v20, v70
	v_pk_mul_f32 v[74:75], v[34:35], v[76:77]
	v_mov_b32_e32 v72, v83
	v_add_f32_e32 v68, v68, v74
	v_add_f32_e32 v90, v70, v71
	v_pk_mul_f32 v[70:71], v[24:25], v[72:73]
	v_add_f32_e32 v76, v68, v75
	v_add_f32_e32 v68, v21, v70
	v_pk_mul_f32 v[74:75], v[8:9], v[72:73]
	v_lshlrev_b32_e32 v69, 16, v132
	v_add_f32_e32 v70, v113, v74
	v_add_f32_e32 v102, v68, v71
	v_mov_b32_e32 v68, v81
	v_add_f32_e32 v72, v70, v75
	v_pk_mul_f32 v[74:75], v[48:49], v[68:69]
	v_and_b32_e32 v67, 0xffff0000, v132
	v_add_f32_e32 v66, v66, v74
	v_pk_mul_f32 v[70:71], v[52:53], v[68:69]
	v_add_f32_e32 v68, v66, v75
	v_mov_b32_e32 v66, v79
	v_pk_mul_f32 v[74:75], v[6:7], v[66:67]
	v_mov_b32_e32 v98, v101
	v_add_f32_e32 v64, v64, v74
	v_add_f32_e32 v64, v64, v75
	v_cvt_pk_bf16_f32 v120, v68, v64
	v_cvt_pk_bf16_f32 v121, v76, v72
	v_cvt_pk_bf16_f32 v122, v82, v88
	v_cvt_pk_bf16_f32 v123, v65, v78
	s_nop 0
	v_mov_b32_e32 v94, v97
	v_mov_b32_e32 v88, v91
	v_add_f32_e32 v70, v18, v70
	v_add_f32_e32 v103, v70, v71
	v_pk_mul_f32 v[70:71], v[22:23], v[66:67]
	v_mov_b32_e32 v82, v87
	v_mov_b32_e32 v78, v77
	v_mov_b32_e32 v74, v73
	v_add_f32_e32 v70, v19, v70
	v_add_f32_e32 v113, v70, v71
	v_mov_b32_e32 v70, v69
	global_store_dwordx4 v[26:27], v[120:123], off
	v_or_b32_e32 v28, 6, v42
	v_ashrrev_i32_e32 v29, 31, v28
	v_lshlrev_b64 v[28:29], 12, v[28:29]
	v_lshl_add_u64 v[26:27], v[46:47], 0, v[58:59]
	v_lshl_add_u64 v[58:59], v[50:51], 0, v[28:29]
	v_lshl_add_u64 v[28:29], v[46:47], 0, v[28:29]
	s_nop 0
	s_waitcnt vmcnt(13)
	v_lshlrev_b32_e32 v99, 16, v139
	v_pk_mul_f32 v[100:101], v[54:55], v[98:99]
	v_and_b32_e32 v95, 0xffff0000, v139
	v_add_f32_e32 v64, v107, v100
	v_add_f32_e32 v81, v64, v101
	v_pk_mul_f32 v[100:101], v[56:57], v[98:99]
	v_pk_mul_f32 v[96:97], v[4:5], v[94:95]
	v_add_f32_e32 v64, v16, v100
	v_add_f32_e32 v107, v64, v101
	v_add_f32_e32 v64, v108, v96
	v_add_f32_e32 v85, v64, v97
	v_pk_mul_f32 v[96:97], v[12:13], v[94:95]
	v_lshlrev_b32_e32 v89, 16, v138
	v_add_f32_e32 v64, v17, v96
	v_add_f32_e32 v108, v64, v97
	v_pk_mul_f32 v[96:97], v[40:41], v[88:89]
	v_pk_mul_f32 v[100:101], v[36:37], v[88:89]
	v_and_b32_e32 v83, 0xffff0000, v138
	v_add_f32_e32 v64, v14, v96
	v_add_f32_e32 v66, v104, v100
	v_lshlrev_b32_e32 v79, 16, v137
	v_add_f32_e32 v91, v66, v101
	v_add_f32_e32 v66, v64, v97
	v_pk_mul_f32 v[96:97], v[10:11], v[82:83]
	v_pk_mul_f32 v[100:101], v[2:3], v[82:83]
	v_add_f32_e32 v64, v15, v96
	v_pk_mul_f32 v[76:77], v[38:39], v[78:79]
	v_and_b32_e32 v75, 0xffff0000, v137
	v_add_f32_e32 v68, v105, v100
	v_add_f32_e32 v88, v64, v97
	v_add_f32_e32 v64, v20, v76
	v_pk_mul_f32 v[96:97], v[34:35], v[78:79]
	v_add_f32_e32 v82, v68, v101
	v_add_f32_e32 v68, v106, v96
	v_add_f32_e32 v104, v64, v77
	v_pk_mul_f32 v[76:77], v[8:9], v[74:75]
	v_lshlrev_b32_e32 v71, 16, v136
	v_add_f32_e32 v78, v68, v97
	v_pk_mul_f32 v[72:73], v[24:25], v[74:75]
	v_add_f32_e32 v68, v112, v76
	v_add_f32_e32 v64, v21, v72
	v_add_f32_e32 v74, v68, v77
	v_pk_mul_f32 v[68:69], v[52:53], v[70:71]
	v_add_f32_e32 v105, v64, v73
	v_add_f32_e32 v64, v18, v68
	v_pk_mul_f32 v[72:73], v[48:49], v[70:71]
	v_and_b32_e32 v65, 0xffff0000, v136
	v_add_f32_e32 v68, v109, v72
	v_add_f32_e32 v106, v64, v69
	v_mov_b32_e32 v64, v67
	v_add_f32_e32 v70, v68, v73
	v_pk_mul_f32 v[72:73], v[6:7], v[64:65]
	v_pk_mul_f32 v[68:69], v[22:23], v[64:65]
	v_add_f32_e32 v64, v92, v72
	v_add_f32_e32 v64, v64, v73
	v_cvt_pk_bf16_f32 v120, v70, v64
	v_cvt_pk_bf16_f32 v121, v78, v74
	v_cvt_pk_bf16_f32 v122, v91, v82
	v_cvt_pk_bf16_f32 v123, v81, v85
	s_nop 0
	v_mov_b32_e32 v96, v99
	v_add_f32_e32 v67, v19, v68
	v_add_f32_e32 v114, v67, v69
	v_mov_b32_e32 v92, v95
	v_mov_b32_e32 v76, v79
	v_mov_b32_e32 v72, v75
	global_store_dwordx4 v[60:61], v[120:123], off
	v_or_b32_e32 v60, 7, v42
	v_ashrrev_i32_e32 v61, 31, v60
	v_lshlrev_b64 v[100:101], 12, v[60:61]
	v_lshl_add_u64 v[60:61], v[50:51], 0, v[100:101]
	s_nop 0
	s_waitcnt vmcnt(13)
; __device__ __forceinline__ void unpack8(const v4u w, float (&f)[8]) { f[0] = bf_lo(w.x); f[1] = bf_hi(w.x); f[2] = bf_lo(w.y); f[3] = bf_hi(w.y); f[4] = bf_lo(w.z); f[5] = bf_hi(w.z); f[6] = bf_lo(w.w); f[7] = bf_hi(w.w); }
; __device__ __forceinline__ v4u pack8(const float (&f)[8]) { v4u w; w.x = cvt_pk_bf16(f[0], f[1]); w.y = cvt_pk_bf16(f[2], f[3]); w.z = cvt_pk_bf16(f[4], f[5]); w.w = cvt_pk_bf16(f[6], f[7]); return w; }
; __device__ __forceinline__ void lru_conv_own(const Frame& F, CArgs* A, int j, const bf16* U, bf16* UC) {
;     ...
;         for (int r = 0; r < 16; ++r) { float x0[8], o[8]; unpack8(*(const v4u*)(U + (size_t)(m0 + r) * 2048 + c), x0);
; #pragma unroll
;             for (int e = 0; e < 8; ++e) o[e] = bias[e] + w[0][e] * x3[e] + w[1][e] * x2[e] + w[2][e] * x1[e] + w[3][e] * x0[e];
;             *(v4u*)(UC + (size_t)(m0 + r) * 2048 + c) = pack8(o);
;             if (t0 + r >= TSEQ - 3) store8f(A->out + O_LCP + ((size_t)(j * 2 + (m0 >> 12)) * 3 + (t0 + r - (TSEQ - 3))) * 2048 + c, x0);
; #pragma unroll
;             for (int e = 0; e < 8; ++e) { x3[e] = x2[e]; x2[e] = x1[e]; x1[e] = x0[e]; } }
	v_lshlrev_b32_e32 v97, 16, v143
	v_pk_mul_f32 v[98:99], v[54:55], v[96:97]
	v_and_b32_e32 v93, 0xffff0000, v143
	v_add_f32_e32 v62, v80, v98
	v_add_f32_e32 v67, v62, v99
	v_pk_mul_f32 v[98:99], v[56:57], v[96:97]
	v_pk_mul_f32 v[94:95], v[4:5], v[92:93]
	v_add_f32_e32 v62, v16, v98
	v_add_f32_e32 v109, v62, v99
	v_add_f32_e32 v62, v84, v94
	v_add_f32_e32 v87, v62, v95
	v_pk_mul_f32 v[94:95], v[12:13], v[92:93]
	v_lshlrev_b32_e32 v85, 16, v142
	v_add_f32_e32 v62, v17, v94
	v_mov_b32_e32 v84, v89
	v_add_f32_e32 v112, v62, v95
	v_pk_mul_f32 v[94:95], v[40:41], v[84:85]
	v_pk_mul_f32 v[98:99], v[36:37], v[84:85]
	v_and_b32_e32 v81, 0xffff0000, v142
	v_add_f32_e32 v62, v14, v94
	v_add_f32_e32 v43, v43, v98
	v_mov_b32_e32 v80, v83
	v_lshlrev_b32_e32 v77, 16, v141
	v_add_f32_e32 v84, v43, v99
	v_add_f32_e32 v43, v62, v95
	v_pk_mul_f32 v[82:83], v[10:11], v[80:81]
	v_pk_mul_f32 v[94:95], v[2:3], v[80:81]
	v_add_f32_e32 v62, v15, v82
	v_add_f32_e32 v64, v86, v94
	v_pk_mul_f32 v[78:79], v[38:39], v[76:77]
	v_and_b32_e32 v73, 0xffff0000, v141
	v_add_f32_e32 v80, v64, v95
	v_add_f32_e32 v64, v62, v83
	v_add_f32_e32 v62, v20, v78
	v_pk_mul_f32 v[82:83], v[34:35], v[76:77]
	v_add_f32_e32 v96, v62, v79
	v_add_f32_e32 v68, v90, v82
	v_pk_mul_f32 v[78:79], v[8:9], v[72:73]
	v_add_f32_e32 v76, v68, v83
	v_add_f32_e32 v68, v102, v78
	v_lshlrev_b32_e32 v69, 16, v140
	v_pk_mul_f32 v[74:75], v[24:25], v[72:73]
	v_add_f32_e32 v72, v68, v79
	v_mov_b32_e32 v68, v71
	v_add_f32_e32 v62, v21, v74
	v_pk_mul_f32 v[70:71], v[52:53], v[68:69]
	v_add_f32_e32 v102, v62, v75
	v_add_f32_e32 v62, v18, v70
	v_pk_mul_f32 v[74:75], v[48:49], v[68:69]
	v_and_b32_e32 v63, 0xffff0000, v140
	v_add_f32_e32 v68, v103, v74
	v_add_f32_e32 v103, v62, v71
	v_mov_b32_e32 v62, v65
	v_add_f32_e32 v68, v68, v75
	v_pk_mul_f32 v[74:75], v[6:7], v[62:63]
	v_pk_mul_f32 v[70:71], v[22:23], v[62:63]
	v_add_f32_e32 v62, v113, v74
	v_add_f32_e32 v62, v62, v75
	v_cvt_pk_bf16_f32 v120, v68, v62
	v_cvt_pk_bf16_f32 v121, v76, v72
	v_cvt_pk_bf16_f32 v122, v84, v80
	v_cvt_pk_bf16_f32 v123, v67, v87
	s_nop 0
	v_mov_b32_e32 v94, v97
	global_store_dwordx4 v[30:31], v[120:123], off
	v_lshl_add_u64 v[30:31], v[46:47], 0, v[100:101]
	v_add_f32_e32 v65, v19, v70
	v_add_f32_e32 v113, v65, v71
	v_mov_b32_e32 v90, v93
	v_mov_b32_e32 v86, v85
	v_mov_b32_e32 v82, v81
	v_mov_b32_e32 v78, v77
	v_mov_b32_e32 v74, v73
	v_mov_b32_e32 v70, v69
	v_or_b32_e32 v32, 8, v42
	v_ashrrev_i32_e32 v33, 31, v32
	v_lshlrev_b64 v[98:99], 12, v[32:33]
	v_lshl_add_u64 v[32:33], v[50:51], 0, v[98:99]
	s_nop 0
	s_waitcnt vmcnt(13)
	v_lshlrev_b32_e32 v95, 16, v147
	v_pk_mul_f32 v[100:101], v[54:55], v[94:95]
	v_and_b32_e32 v91, 0xffff0000, v147
	v_add_f32_e32 v62, v107, v100
	v_add_f32_e32 v65, v62, v101
	v_pk_mul_f32 v[100:101], v[56:57], v[94:95]
	v_pk_mul_f32 v[92:93], v[4:5], v[90:91]
	v_add_f32_e32 v62, v16, v100
	v_add_f32_e32 v107, v62, v101
	v_add_f32_e32 v62, v108, v92
	v_lshlrev_b32_e32 v87, 16, v146
	v_add_f32_e32 v89, v62, v93
	v_pk_mul_f32 v[92:93], v[12:13], v[90:91]
	v_and_b32_e32 v83, 0xffff0000, v146
	v_add_f32_e32 v62, v17, v92
	v_pk_mul_f32 v[84:85], v[40:41], v[86:87]
	v_lshlrev_b32_e32 v79, 16, v145
	v_add_f32_e32 v108, v62, v93
	v_add_f32_e32 v62, v14, v84
	v_pk_mul_f32 v[92:93], v[36:37], v[86:87]
	v_pk_mul_f32 v[80:81], v[10:11], v[82:83]
	v_and_b32_e32 v75, 0xffff0000, v145
	v_add_f32_e32 v66, v66, v92
	v_add_f32_e32 v97, v62, v85
	v_add_f32_e32 v62, v15, v80
	v_pk_mul_f32 v[84:85], v[2:3], v[82:83]
	v_pk_mul_f32 v[76:77], v[38:39], v[78:79]
	v_add_f32_e32 v86, v66, v93
	v_add_f32_e32 v66, v88, v84
	v_add_f32_e32 v100, v62, v81
	v_add_f32_e32 v62, v20, v76
	v_pk_mul_f32 v[80:81], v[34:35], v[78:79]
	v_pk_mul_f32 v[72:73], v[24:25], v[74:75]
	v_lshlrev_b32_e32 v71, 16, v144
	v_add_f32_e32 v82, v66, v85
	v_add_f32_e32 v66, v104, v80
	v_add_f32_e32 v101, v62, v77
	v_add_f32_e32 v62, v21, v72
	v_pk_mul_f32 v[76:77], v[8:9], v[74:75]
	v_add_f32_e32 v78, v66, v81
	v_add_f32_e32 v66, v105, v76
	v_add_f32_e32 v104, v62, v73
	v_pk_mul_f32 v[72:73], v[48:49], v[70:71]
	v_add_f32_e32 v74, v66, v77
	v_pk_mul_f32 v[68:69], v[52:53], v[70:71]
	v_add_f32_e32 v66, v106, v72
	v_and_b32_e32 v67, 0xffff0000, v144
	v_add_f32_e32 v62, v18, v68
	v_add_f32_e32 v70, v66, v73
	v_mov_b32_e32 v66, v63
	v_add_f32_e32 v105, v62, v69
	v_pk_mul_f32 v[68:69], v[6:7], v[66:67]
	v_pk_mul_f32 v[62:63], v[22:23], v[66:67]
	v_add_f32_e32 v66, v114, v68
	v_add_f32_e32 v66, v66, v69
	v_cvt_pk_bf16_f32 v120, v70, v66
	v_cvt_pk_bf16_f32 v121, v78, v74
	v_cvt_pk_bf16_f32 v122, v86, v82
	v_cvt_pk_bf16_f32 v123, v65, v89
	s_nop 0
	v_mov_b32_e32 v92, v95
	global_store_dwordx4 v[26:27], v[120:123], off
	v_lshl_add_u64 v[26:27], v[46:47], 0, v[98:99]
	v_mov_b32_e32 v88, v91
	v_mov_b32_e32 v84, v87
	v_mov_b32_e32 v80, v83
	v_mov_b32_e32 v76, v79
	v_mov_b32_e32 v72, v75
	v_mov_b32_e32 v68, v71
	v_add_f32_e32 v62, v19, v62
	v_add_f32_e32 v106, v62, v63
	v_or_b32_e32 v58, 9, v42
	v_ashrrev_i32_e32 v59, 31, v58
	v_lshlrev_b64 v[58:59], 12, v[58:59]
	v_lshl_add_u64 v[62:63], v[50:51], 0, v[58:59]
	v_lshl_add_u64 v[58:59], v[46:47], 0, v[58:59]
	s_nop 0
	s_waitcnt vmcnt(13)
; __device__ __forceinline__ void unpack8(const v4u w, float (&f)[8]) { f[0] = bf_lo(w.x); f[1] = bf_hi(w.x); f[2] = bf_lo(w.y); f[3] = bf_hi(w.y); f[4] = bf_lo(w.z); f[5] = bf_hi(w.z); f[6] = bf_lo(w.w); f[7] = bf_hi(w.w); }
; __device__ __forceinline__ v4u pack8(const float (&f)[8]) { v4u w; w.x = cvt_pk_bf16(f[0], f[1]); w.y = cvt_pk_bf16(f[2], f[3]); w.z = cvt_pk_bf16(f[4], f[5]); w.w = cvt_pk_bf16(f[6], f[7]); return w; }
; __device__ __forceinline__ void lru_conv_own(const Frame& F, CArgs* A, int j, const bf16* U, bf16* UC) {
;     ...
;         for (int r = 0; r < 16; ++r) { float x0[8], o[8]; unpack8(*(const v4u*)(U + (size_t)(m0 + r) * 2048 + c), x0);
; #pragma unroll
;             for (int e = 0; e < 8; ++e) o[e] = bias[e] + w[0][e] * x3[e] + w[1][e] * x2[e] + w[2][e] * x1[e] + w[3][e] * x0[e];
;             *(v4u*)(UC + (size_t)(m0 + r) * 2048 + c) = pack8(o);
;             if (t0 + r >= TSEQ - 3) store8f(A->out + O_LCP + ((size_t)(j * 2 + (m0 >> 12)) * 3 + (t0 + r - (TSEQ - 3))) * 2048 + c, x0);
; #pragma unroll
;             for (int e = 0; e < 8; ++e) { x3[e] = x2[e]; x2[e] = x1[e]; x1[e] = x0[e]; } }
	v_lshlrev_b32_e32 v93, 16, v151
	v_pk_mul_f32 v[94:95], v[54:55], v[92:93]
	v_and_b32_e32 v89, 0xffff0000, v151
	v_add_f32_e32 v66, v109, v94
	v_add_f32_e32 v99, v66, v95
	v_pk_mul_f32 v[94:95], v[56:57], v[92:93]
	v_pk_mul_f32 v[90:91], v[4:5], v[88:89]
	v_add_f32_e32 v66, v16, v94
	v_add_f32_e32 v92, v66, v95
	v_add_f32_e32 v66, v112, v90
	v_lshlrev_b32_e32 v85, 16, v150
	v_add_f32_e32 v94, v66, v91
	v_pk_mul_f32 v[90:91], v[12:13], v[88:89]
	v_pk_mul_f32 v[86:87], v[40:41], v[84:85]
	v_add_f32_e32 v66, v17, v90
	v_and_b32_e32 v81, 0xffff0000, v150
	v_add_f32_e32 v88, v66, v91
	v_add_f32_e32 v66, v14, v86
	v_lshlrev_b32_e32 v77, 16, v149
	v_pk_mul_f32 v[90:91], v[36:37], v[84:85]
	v_add_f32_e32 v84, v66, v87
	v_pk_mul_f32 v[86:87], v[2:3], v[80:81]
	v_and_b32_e32 v73, 0xffff0000, v149
	v_pk_mul_f32 v[82:83], v[10:11], v[80:81]
	v_add_f32_e32 v64, v64, v86
	v_pk_mul_f32 v[78:79], v[38:39], v[76:77]
	v_lshlrev_b32_e32 v69, 16, v148
	v_add_f32_e32 v66, v15, v82
	v_add_f32_e32 v86, v64, v87
	v_add_f32_e32 v64, v20, v78
	v_pk_mul_f32 v[74:75], v[24:25], v[72:73]
	v_add_f32_e32 v80, v66, v83
	v_pk_mul_f32 v[82:83], v[34:35], v[76:77]
	v_add_f32_e32 v76, v64, v79
	v_add_f32_e32 v64, v21, v74
	v_pk_mul_f32 v[70:71], v[52:53], v[68:69]
	v_add_f32_e32 v66, v96, v82
	v_pk_mul_f32 v[78:79], v[8:9], v[72:73]
	v_add_f32_e32 v72, v64, v75
	v_add_f32_e32 v64, v18, v70
	v_and_b32_e32 v65, 0xffff0000, v148
	v_add_f32_e32 v82, v66, v83
	v_add_f32_e32 v66, v102, v78
	v_pk_mul_f32 v[74:75], v[48:49], v[68:69]
	v_add_f32_e32 v68, v64, v71
	v_mov_b32_e32 v64, v67
	v_add_f32_e32 v78, v66, v79
	v_add_f32_e32 v66, v103, v74
	v_pk_mul_f32 v[70:71], v[6:7], v[64:65]
	v_add_f32_e32 v43, v43, v90
	v_add_f32_e32 v74, v66, v75
	v_pk_mul_f32 v[66:67], v[22:23], v[64:65]
	v_add_f32_e32 v64, v113, v70
	v_add_f32_e32 v43, v43, v91
	v_add_f32_e32 v64, v64, v71
	v_cvt_pk_bf16_f32 v112, v74, v64
	v_cvt_pk_bf16_f32 v113, v82, v78
	v_cvt_pk_bf16_f32 v114, v43, v86
	v_cvt_pk_bf16_f32 v115, v99, v94
	s_nop 0
	v_mov_b32_e32 v90, v93
	global_store_dwordx4 v[28:29], v[112:115], off
	v_mov_b32_e32 v86, v85
	v_mov_b32_e32 v82, v81
	v_mov_b32_e32 v78, v77
	v_mov_b32_e32 v74, v73
	v_mov_b32_e32 v70, v69
	v_add_f32_e32 v66, v19, v66
	v_add_f32_e32 v98, v66, v67
	v_mov_b32_e32 v66, v65
	v_or_b32_e32 v60, 10, v42
	v_ashrrev_i32_e32 v61, 31, v60
	v_lshlrev_b64 v[94:95], 12, v[60:61]
	v_lshl_add_u64 v[60:61], v[50:51], 0, v[94:95]
	s_nop 0
	s_waitcnt vmcnt(13)
	v_lshlrev_b32_e32 v91, 16, v155
	v_pk_mul_f32 v[102:103], v[54:55], v[90:91]
	v_and_b32_e32 v29, 0xffff0000, v155
	v_add_f32_e32 v28, v107, v102
	v_add_f32_e32 v93, v28, v103
	v_pk_mul_f32 v[102:103], v[56:57], v[90:91]
	v_lshlrev_b32_e32 v87, 16, v154
	v_add_f32_e32 v28, v16, v102
	v_add_f32_e32 v43, v28, v103
	v_mov_b32_e32 v28, v89
	v_pk_mul_f32 v[102:103], v[4:5], v[28:29]
	v_and_b32_e32 v83, 0xffff0000, v154
	v_add_f32_e32 v64, v108, v102
	v_add_f32_e32 v89, v64, v103
	v_pk_mul_f32 v[102:103], v[12:13], v[28:29]
	v_pk_mul_f32 v[108:109], v[36:37], v[86:87]
	v_add_f32_e32 v28, v17, v102
	v_add_f32_e32 v90, v28, v103
	v_pk_mul_f32 v[102:103], v[40:41], v[86:87]
	v_add_f32_e32 v64, v97, v108
	v_add_f32_e32 v28, v14, v102
	v_pk_mul_f32 v[96:97], v[10:11], v[82:83]
	v_lshlrev_b32_e32 v79, 16, v153
	v_add_f32_e32 v86, v28, v103
	v_add_f32_e32 v28, v15, v96
	v_pk_mul_f32 v[102:103], v[2:3], v[82:83]
	v_add_f32_e32 v85, v64, v109
	v_add_f32_e32 v64, v100, v102
	v_add_f32_e32 v82, v28, v97
	v_pk_mul_f32 v[96:97], v[38:39], v[78:79]
	v_and_b32_e32 v75, 0xffff0000, v153
	v_add_f32_e32 v81, v64, v103
	v_add_f32_e32 v28, v20, v96
	v_pk_mul_f32 v[102:103], v[34:35], v[78:79]
	v_add_f32_e32 v78, v28, v97
	v_add_f32_e32 v64, v101, v102
	v_pk_mul_f32 v[96:97], v[24:25], v[74:75]
	v_pk_mul_f32 v[100:101], v[8:9], v[74:75]
	v_lshlrev_b32_e32 v71, 16, v152
	v_add_f32_e32 v77, v64, v103
	v_add_f32_e32 v28, v21, v96
	v_add_f32_e32 v64, v104, v100
	v_add_f32_e32 v73, v64, v101
	v_add_f32_e32 v74, v28, v97
	v_pk_mul_f32 v[96:97], v[52:53], v[70:71]
	v_pk_mul_f32 v[100:101], v[48:49], v[70:71]
	v_and_b32_e32 v67, 0xffff0000, v152
	v_add_f32_e32 v28, v18, v96
	v_add_f32_e32 v64, v105, v100
	v_add_f32_e32 v69, v64, v101
	v_add_f32_e32 v70, v28, v97
	v_pk_mul_f32 v[64:65], v[22:23], v[66:67]
	v_pk_mul_f32 v[96:97], v[6:7], v[66:67]
	v_add_f32_e32 v28, v19, v64
	v_add_f32_e32 v64, v106, v96
	v_add_f32_e32 v64, v64, v97
	v_cvt_pk_bf16_f32 v104, v69, v64
	v_cvt_pk_bf16_f32 v105, v77, v73
	v_cvt_pk_bf16_f32 v106, v85, v81
	v_cvt_pk_bf16_f32 v107, v93, v89
	s_nop 0
	v_mov_b32_e32 v96, v91
	v_lshl_add_u64 v[32:33], v[46:47], 0, v[94:95]
	v_add_f32_e32 v103, v28, v65
	global_store_dwordx4 v[30:31], v[104:107], off
	v_or_b32_e32 v30, 11, v42
	v_ashrrev_i32_e32 v31, 31, v30
	v_lshlrev_b64 v[30:31], 12, v[30:31]
	v_lshl_add_u64 v[64:65], v[50:51], 0, v[30:31]
	s_nop 0
	s_waitcnt vmcnt(13)
; __device__ __forceinline__ void unpack8(const v4u w, float (&f)[8]) { f[0] = bf_lo(w.x); f[1] = bf_hi(w.x); f[2] = bf_lo(w.y); f[3] = bf_hi(w.y); f[4] = bf_lo(w.z); f[5] = bf_hi(w.z); f[6] = bf_lo(w.w); f[7] = bf_hi(w.w); }
; __device__ __forceinline__ v4u pack8(const float (&f)[8]) { v4u w; w.x = cvt_pk_bf16(f[0], f[1]); w.y = cvt_pk_bf16(f[2], f[3]); w.z = cvt_pk_bf16(f[4], f[5]); w.w = cvt_pk_bf16(f[6], f[7]); return w; }
; __device__ __forceinline__ void lru_conv_own(const Frame& F, CArgs* A, int j, const bf16* U, bf16* UC) {
;     ...
;         for (int r = 0; r < 16; ++r) { float x0[8], o[8]; unpack8(*(const v4u*)(U + (size_t)(m0 + r) * 2048 + c), x0);
; #pragma unroll
;             for (int e = 0; e < 8; ++e) o[e] = bias[e] + w[0][e] * x3[e] + w[1][e] * x2[e] + w[2][e] * x1[e] + w[3][e] * x0[e];
;             *(v4u*)(UC + (size_t)(m0 + r) * 2048 + c) = pack8(o);
;             if (t0 + r >= TSEQ - 3) store8f(A->out + O_LCP + ((size_t)(j * 2 + (m0 >> 12)) * 3 + (t0 + r - (TSEQ - 3))) * 2048 + c, x0);
; #pragma unroll
;             for (int e = 0; e < 8; ++e) { x3[e] = x2[e]; x2[e] = x1[e]; x1[e] = x0[e]; } }
	v_lshlrev_b32_e32 v97, 16, v159
	v_pk_mul_f32 v[94:95], v[54:55], v[96:97]
	v_and_b32_e32 v93, 0xffff0000, v159
	v_add_f32_e32 v28, v92, v94
	v_add_f32_e32 v91, v28, v95
	v_pk_mul_f32 v[94:95], v[56:57], v[96:97]
	v_mov_b32_e32 v92, v29
	v_add_f32_e32 v28, v16, v94
	v_add_f32_e32 v96, v28, v95
	v_pk_mul_f32 v[28:29], v[4:5], v[92:93]
	v_lshlrev_b32_e32 v89, 16, v158
	v_add_f32_e32 v28, v88, v28
	v_mov_b32_e32 v88, v87
	v_pk_mul_f32 v[94:95], v[36:37], v[88:89]
	v_and_b32_e32 v85, 0xffff0000, v158
	v_add_f32_e32 v66, v84, v94
	v_mov_b32_e32 v84, v83
	v_add_f32_e32 v87, v66, v95
	v_pk_mul_f32 v[94:95], v[2:3], v[84:85]
	v_lshlrev_b32_e32 v81, 16, v157
	v_add_f32_e32 v66, v80, v94
	v_mov_b32_e32 v80, v79
	v_add_f32_e32 v83, v66, v95
	v_pk_mul_f32 v[94:95], v[34:35], v[80:81]
	v_and_b32_e32 v77, 0xffff0000, v157
	v_add_f32_e32 v66, v76, v94
	v_mov_b32_e32 v76, v75
	v_add_f32_e32 v79, v66, v95
	v_pk_mul_f32 v[94:95], v[8:9], v[76:77]
	v_lshlrev_b32_e32 v73, 16, v156
	v_add_f32_e32 v66, v72, v94
	v_mov_b32_e32 v72, v71
	v_add_f32_e32 v75, v66, v95
	v_pk_mul_f32 v[94:95], v[48:49], v[72:73]
	v_and_b32_e32 v69, 0xffff0000, v156
	v_add_f32_e32 v66, v68, v94
	v_mov_b32_e32 v68, v67
	v_add_f32_e32 v71, v66, v95
	v_pk_mul_f32 v[66:67], v[6:7], v[68:69]
	v_add_f32_e32 v99, v28, v29
	v_add_f32_e32 v66, v98, v66
	v_add_f32_e32 v66, v66, v67
	v_cvt_pk_bf16_f32 v106, v71, v66
	v_cvt_pk_bf16_f32 v107, v79, v75
	v_cvt_pk_bf16_f32 v108, v87, v83
	v_cvt_pk_bf16_f32 v109, v91, v99
	s_nop 0
	v_pk_mul_f32 v[28:29], v[12:13], v[92:93]
	v_mov_b32_e32 v98, v97
	v_add_f32_e32 v28, v17, v28
	v_add_f32_e32 v92, v28, v29
	v_pk_mul_f32 v[28:29], v[40:41], v[88:89]
	global_store_dwordx4 v[26:27], v[106:109], off
	v_add_f32_e32 v28, v14, v28
	v_add_f32_e32 v88, v28, v29
	v_pk_mul_f32 v[28:29], v[10:11], v[84:85]
	v_mov_b32_e32 v94, v93
	v_add_f32_e32 v28, v15, v28
	v_add_f32_e32 v84, v28, v29
	v_pk_mul_f32 v[28:29], v[38:39], v[80:81]
	v_or_b32_e32 v26, 12, v42
	v_add_f32_e32 v28, v20, v28
	v_add_f32_e32 v80, v28, v29
	v_pk_mul_f32 v[28:29], v[24:25], v[76:77]
	v_ashrrev_i32_e32 v27, 31, v26
	v_add_f32_e32 v28, v21, v28
	v_add_f32_e32 v101, v28, v29
	v_pk_mul_f32 v[28:29], v[52:53], v[72:73]
	v_lshlrev_b64 v[26:27], 12, v[26:27]
	v_add_f32_e32 v28, v18, v28
	v_add_f32_e32 v102, v28, v29
	v_pk_mul_f32 v[28:29], v[22:23], v[68:69]
	v_lshl_add_u64 v[66:67], v[50:51], 0, v[26:27]
	v_add_f32_e32 v28, v19, v28
	v_add_f32_e32 v105, v28, v29
	v_lshl_add_u64 v[62:63], v[46:47], 0, v[30:31]
	v_lshl_add_u64 v[28:29], v[46:47], 0, v[26:27]
	v_or_b32_e32 v26, 13, v42
	v_ashrrev_i32_e32 v27, 31, v26
	v_lshlrev_b64 v[26:27], 12, v[26:27]
	v_lshl_add_u64 v[30:31], v[50:51], 0, v[26:27]
	v_lshl_add_u64 v[26:27], v[46:47], 0, v[26:27]
	s_nop 0
	s_waitcnt vmcnt(13)
	v_lshlrev_b32_e32 v99, 16, v163
	v_pk_mul_f32 v[106:107], v[54:55], v[98:99]
	v_and_b32_e32 v95, 0xffff0000, v163
	v_add_f32_e32 v43, v43, v106
	v_add_f32_e32 v97, v43, v107
	v_pk_mul_f32 v[106:107], v[56:57], v[98:99]
	v_lshlrev_b32_e32 v91, 16, v162
	v_add_f32_e32 v43, v16, v106
	v_add_f32_e32 v100, v43, v107
	v_pk_mul_f32 v[106:107], v[4:5], v[94:95]
	v_and_b32_e32 v87, 0xffff0000, v162
	v_add_f32_e32 v43, v90, v106
	v_add_f32_e32 v93, v43, v107
	v_pk_mul_f32 v[106:107], v[12:13], v[94:95]
	v_mov_b32_e32 v90, v89
	v_add_f32_e32 v43, v17, v106
	v_add_f32_e32 v43, v43, v107
	v_pk_mul_f32 v[106:107], v[40:41], v[90:91]
	v_pk_mul_f32 v[108:109], v[36:37], v[90:91]
	v_add_f32_e32 v68, v14, v106
	v_add_f32_e32 v72, v86, v108
	v_mov_b32_e32 v86, v85
	v_add_f32_e32 v89, v72, v109
	v_add_f32_e32 v98, v68, v107
	v_pk_mul_f32 v[106:107], v[10:11], v[86:87]
	v_pk_mul_f32 v[108:109], v[2:3], v[86:87]
	v_lshlrev_b32_e32 v83, 16, v161
	v_add_f32_e32 v68, v15, v106
	v_add_f32_e32 v72, v82, v108
	v_mov_b32_e32 v82, v81
	v_add_f32_e32 v85, v72, v109
	v_add_f32_e32 v86, v68, v107
	v_pk_mul_f32 v[106:107], v[38:39], v[82:83]
	v_pk_mul_f32 v[108:109], v[34:35], v[82:83]
	v_and_b32_e32 v79, 0xffff0000, v161
	v_add_f32_e32 v68, v20, v106
	v_add_f32_e32 v72, v78, v108
	v_mov_b32_e32 v78, v77
	v_add_f32_e32 v104, v68, v107
	v_pk_mul_f32 v[76:77], v[24:25], v[78:79]
	v_pk_mul_f32 v[106:107], v[8:9], v[78:79]
	v_lshlrev_b32_e32 v75, 16, v160
	v_add_f32_e32 v81, v72, v109
	v_add_f32_e32 v68, v21, v76
	v_add_f32_e32 v72, v74, v106
	v_mov_b32_e32 v74, v73
	v_add_f32_e32 v106, v68, v77
	v_pk_mul_f32 v[76:77], v[48:49], v[74:75]
	v_add_f32_e32 v78, v72, v107
	v_pk_mul_f32 v[72:73], v[52:53], v[74:75]
	v_add_f32_e32 v70, v70, v76
	v_and_b32_e32 v71, 0xffff0000, v160
	v_add_f32_e32 v68, v18, v72
	v_add_f32_e32 v74, v70, v77
	v_mov_b32_e32 v70, v69
	v_add_f32_e32 v107, v68, v73
	v_pk_mul_f32 v[72:73], v[6:7], v[70:71]
	v_pk_mul_f32 v[68:69], v[22:23], v[70:71]
	v_add_f32_e32 v70, v103, v72
	v_add_f32_e32 v70, v70, v73
	v_cvt_pk_bf16_f32 v112, v74, v70
	v_cvt_pk_bf16_f32 v113, v81, v78
	v_cvt_pk_bf16_f32 v114, v89, v85
	v_cvt_pk_bf16_f32 v115, v97, v93
	s_nop 0
	v_add_f32_e32 v68, v19, v68
	global_store_dwordx4 v[58:59], v[112:115], off
	v_mov_b32_e32 v58, v99
	v_add_f32_e32 v109, v68, v69
	v_mov_b32_e32 v72, v87
	v_mov_b32_e32 v76, v83
	s_nop 0
	s_waitcnt vmcnt(13)
; __device__ __forceinline__ void unpack8(const v4u w, float (&f)[8]) { f[0] = bf_lo(w.x); f[1] = bf_hi(w.x); f[2] = bf_lo(w.y); f[3] = bf_hi(w.y); f[4] = bf_lo(w.z); f[5] = bf_hi(w.z); f[6] = bf_lo(w.w); f[7] = bf_hi(w.w); }
; __device__ __forceinline__ v4u pack8(const float (&f)[8]) { v4u w; w.x = cvt_pk_bf16(f[0], f[1]); w.y = cvt_pk_bf16(f[2], f[3]); w.z = cvt_pk_bf16(f[4], f[5]); w.w = cvt_pk_bf16(f[6], f[7]); return w; }
; __device__ __forceinline__ void lru_conv_own(const Frame& F, CArgs* A, int j, const bf16* U, bf16* UC) {
;     ...
;         for (int r = 0; r < 16; ++r) { float x0[8], o[8]; unpack8(*(const v4u*)(U + (size_t)(m0 + r) * 2048 + c), x0);
; #pragma unroll
;             for (int e = 0; e < 8; ++e) o[e] = bias[e] + w[0][e] * x3[e] + w[1][e] * x2[e] + w[2][e] * x1[e] + w[3][e] * x0[e];
;             *(v4u*)(UC + (size_t)(m0 + r) * 2048 + c) = pack8(o);
;             if (t0 + r >= TSEQ - 3) store8f(A->out + O_LCP + ((size_t)(j * 2 + (m0 >> 12)) * 3 + (t0 + r - (TSEQ - 3))) * 2048 + c, x0);
; #pragma unroll
;             for (int e = 0; e < 8; ++e) { x3[e] = x2[e]; x2[e] = x1[e]; x1[e] = x0[e]; } }
	v_lshlrev_b32_e32 v59, 16, v167
	v_pk_mul_f32 v[112:113], v[56:57], v[58:59]
	v_pk_mul_f32 v[114:115], v[54:55], v[58:59]
	v_add_f32_e32 v60, v16, v112
	v_add_f32_e32 v58, v96, v114
	v_and_b32_e32 v61, 0xffff0000, v167
	v_add_f32_e32 v115, v58, v115
	v_add_f32_e32 v58, v60, v113
	v_mov_b32_e32 v60, v95
	v_pk_mul_f32 v[94:95], v[12:13], v[60:61]
	v_lshlrev_b32_e32 v69, 16, v166
	v_add_f32_e32 v68, v17, v94
	v_pk_mul_f32 v[96:97], v[4:5], v[60:61]
	v_add_f32_e32 v99, v68, v95
	v_mov_b32_e32 v68, v91
	v_add_f32_e32 v60, v92, v96
	v_pk_mul_f32 v[90:91], v[40:41], v[68:69]
	v_pk_mul_f32 v[92:93], v[36:37], v[68:69]
	v_and_b32_e32 v73, 0xffff0000, v166
	v_add_f32_e32 v70, v14, v90
	v_add_f32_e32 v68, v88, v92
	v_add_f32_e32 v94, v68, v93
	v_add_f32_e32 v68, v70, v91
	v_pk_mul_f32 v[90:91], v[10:11], v[72:73]
	v_lshlrev_b32_e32 v77, 16, v165
	v_add_f32_e32 v70, v15, v90
	v_add_f32_e32 v103, v70, v91
	v_pk_mul_f32 v[82:83], v[38:39], v[76:77]
	v_pk_mul_f32 v[90:91], v[34:35], v[76:77]
	v_and_b32_e32 v81, 0xffff0000, v165
	v_add_f32_e32 v70, v20, v82
	v_add_f32_e32 v74, v80, v90
	v_mov_b32_e32 v80, v79
	v_pk_mul_f32 v[92:93], v[2:3], v[72:73]
	v_add_f32_e32 v108, v70, v83
	v_pk_mul_f32 v[78:79], v[24:25], v[80:81]
	v_pk_mul_f32 v[82:83], v[8:9], v[80:81]
	v_lshlrev_b32_e32 v85, 16, v164
	v_add_f32_e32 v72, v84, v92
	v_add_f32_e32 v76, v74, v91
	v_add_f32_e32 v70, v21, v78
	v_add_f32_e32 v74, v101, v82
	v_mov_b32_e32 v84, v75
	v_add_f32_e32 v80, v74, v83
	v_add_f32_e32 v101, v70, v79
	v_pk_mul_f32 v[74:75], v[52:53], v[84:85]
	v_pk_mul_f32 v[78:79], v[48:49], v[84:85]
	v_and_b32_e32 v89, 0xffff0000, v164
	v_add_f32_e32 v70, v18, v74
	v_add_f32_e32 v74, v102, v78
	v_mov_b32_e32 v88, v71
	v_add_f32_e32 v78, v74, v79
	v_add_f32_e32 v102, v70, v75
	v_pk_mul_f32 v[74:75], v[6:7], v[88:89]
	v_add_f32_e32 v60, v60, v97
	v_add_f32_e32 v74, v105, v74
	v_add_f32_e32 v72, v72, v93
	v_add_f32_e32 v74, v74, v75
	v_cvt_pk_bf16_f32 v112, v78, v74
	v_cvt_pk_bf16_f32 v113, v76, v80
	v_cvt_pk_bf16_f32 v114, v94, v72
	v_cvt_pk_bf16_f32 v115, v115, v60
	s_nop 0
	v_mov_b32_e32 v74, v85
	v_mov_b32_e32 v84, v61
	v_mov_b32_e32 v82, v73
	v_mov_b32_e32 v72, v69
	global_store_dwordx4 v[32:33], v[112:115], off
	v_mov_b32_e32 v32, v59
	v_mov_b32_e32 v78, v81
	v_mov_b32_e32 v80, v77
	v_pk_mul_f32 v[70:71], v[22:23], v[88:89]
	s_nop 0
	s_waitcnt vmcnt(13)
	v_and_b32_e32 v85, 0xffff0000, v173
	v_pk_mul_f32 v[60:61], v[4:5], v[84:85]
	v_lshlrev_b32_e32 v73, 16, v172
	v_add_f32_e32 v43, v43, v60
	v_lshlrev_b32_e32 v33, 16, v173
	v_add_f32_e32 v43, v43, v61
	v_pk_mul_f32 v[60:61], v[36:37], v[72:73]
	v_and_b32_e32 v83, 0xffff0000, v172
	v_pk_mul_f32 v[64:65], v[54:55], v[32:33]
	v_add_f32_e32 v60, v98, v60
	v_add_f32_e32 v59, v100, v64
	v_add_f32_e32 v64, v60, v61
	v_pk_mul_f32 v[60:61], v[2:3], v[82:83]
	v_lshlrev_b32_e32 v81, 16, v171
	v_add_f32_e32 v60, v86, v60
	v_add_f32_e32 v59, v59, v65
	v_add_f32_e32 v65, v60, v61
	v_pk_mul_f32 v[60:61], v[34:35], v[80:81]
	v_and_b32_e32 v79, 0xffff0000, v171
	v_add_f32_e32 v60, v104, v60
	v_add_f32_e32 v69, v60, v61
	v_pk_mul_f32 v[60:61], v[8:9], v[78:79]
	v_lshlrev_b32_e32 v75, 16, v170
	v_add_f32_e32 v60, v106, v60
	v_add_f32_e32 v70, v19, v70
	v_pk_mul_f32 v[126:127], v[40:41], v[72:73]
	v_add_f32_e32 v72, v60, v61
	v_pk_mul_f32 v[60:61], v[48:49], v[74:75]
	v_add_f32_e32 v105, v70, v71
	v_and_b32_e32 v71, 0xffff0000, v170
	v_mov_b32_e32 v70, v89
	v_add_f32_e32 v60, v107, v60
	v_pk_mul_f32 v[92:93], v[52:53], v[74:75]
	v_add_f32_e32 v74, v60, v61
	v_pk_mul_f32 v[60:61], v[6:7], v[70:71]
	v_pk_mul_f32 v[90:91], v[22:23], v[70:71]
	v_add_f32_e32 v60, v109, v60
	v_add_f32_e32 v60, v60, v61
	v_cvt_pk_bf16_f32 v112, v74, v60
	v_cvt_pk_bf16_f32 v113, v69, v72
	v_cvt_pk_bf16_f32 v114, v64, v65
	v_cvt_pk_bf16_f32 v115, v59, v43
	s_nop 0
	v_mov_b32_e32 v60, v33
	global_store_dwordx4 v[62:63], v[112:115], off
	v_pk_mul_f32 v[62:63], v[56:57], v[32:33]
	v_mov_b32_e32 v66, v73
	v_add_f32_e32 v32, v16, v62
	v_add_f32_e32 v62, v32, v63
	v_mov_b32_e32 v64, v83
	v_add_f32_e32 v76, v19, v90
	v_add_f32_e32 v70, v76, v91
	v_mov_b32_e32 v76, v81
	v_pk_mul_f32 v[96:97], v[38:39], v[80:81]
	v_add_f32_e32 v88, v18, v92
	v_add_f32_e32 v43, v88, v93
	v_mov_b32_e32 v88, v75
	v_pk_mul_f32 v[94:95], v[24:25], v[78:79]
	v_mov_b32_e32 v86, v71
	v_add_f32_e32 v90, v21, v94
	v_add_f32_e32 v92, v20, v96
	v_add_f32_e32 v72, v92, v97
	v_add_f32_e32 v78, v90, v95
	v_pk_mul_f32 v[124:125], v[10:11], v[82:83]
	v_add_f32_e32 v96, v14, v126
	v_add_f32_e32 v94, v15, v124
	v_add_f32_e32 v106, v94, v125
	v_add_f32_e32 v104, v96, v127
	s_nop 0
	s_waitcnt vmcnt(13)
; __device__ __forceinline__ void unpack8(const v4u w, float (&f)[8]) { f[0] = bf_lo(w.x); f[1] = bf_hi(w.x); f[2] = bf_lo(w.y); f[3] = bf_hi(w.y); f[4] = bf_lo(w.z); f[5] = bf_hi(w.z); f[6] = bf_lo(w.w); f[7] = bf_hi(w.w); }
; __device__ __forceinline__ v4u pack8(const float (&f)[8]) { v4u w; w.x = cvt_pk_bf16(f[0], f[1]); w.y = cvt_pk_bf16(f[2], f[3]); w.z = cvt_pk_bf16(f[4], f[5]); w.w = cvt_pk_bf16(f[6], f[7]); return w; }
; __device__ __forceinline__ void lru_conv_own(const Frame& F, CArgs* A, int j, const bf16* U, bf16* UC) {
;     ...
;         for (int r = 0; r < 16; ++r) { float x0[8], o[8]; unpack8(*(const v4u*)(U + (size_t)(m0 + r) * 2048 + c), x0);
; #pragma unroll
;             for (int e = 0; e < 8; ++e) o[e] = bias[e] + w[0][e] * x3[e] + w[1][e] * x2[e] + w[2][e] * x1[e] + w[3][e] * x0[e];
;             *(v4u*)(UC + (size_t)(m0 + r) * 2048 + c) = pack8(o);
;             if (t0 + r >= TSEQ - 3) store8f(A->out + O_LCP + ((size_t)(j * 2 + (m0 >> 12)) * 3 + (t0 + r - (TSEQ - 3))) * 2048 + c, x0);
; #pragma unroll
;             for (int e = 0; e < 8; ++e) { x3[e] = x2[e]; x2[e] = x1[e]; x1[e] = x0[e]; } }
	v_lshlrev_b32_e32 v61, 16, v179
	v_pk_mul_f32 v[32:33], v[54:55], v[60:61]
	v_and_b32_e32 v59, 0xffff0000, v179
	v_add_f32_e32 v32, v58, v32
	v_add_f32_e32 v63, v32, v33
	v_pk_mul_f32 v[32:33], v[12:13], v[84:85]
	v_mov_b32_e32 v58, v85
	v_add_f32_e32 v32, v17, v32
	v_add_f32_e32 v107, v32, v33
	v_pk_mul_f32 v[32:33], v[4:5], v[58:59]
	v_lshlrev_b32_e32 v67, 16, v178
	v_add_f32_e32 v32, v99, v32
	v_add_f32_e32 v74, v32, v33
	v_pk_mul_f32 v[32:33], v[36:37], v[66:67]
	v_and_b32_e32 v65, 0xffff0000, v178
	v_add_f32_e32 v32, v68, v32
	v_add_f32_e32 v73, v32, v33
	v_pk_mul_f32 v[32:33], v[2:3], v[64:65]
	v_lshlrev_b32_e32 v77, 16, v177
	v_add_f32_e32 v32, v103, v32
	v_add_f32_e32 v80, v32, v33
	v_pk_mul_f32 v[32:33], v[34:35], v[76:77]
	v_and_b32_e32 v69, 0xffff0000, v177
	v_add_f32_e32 v32, v108, v32
	v_mov_b32_e32 v68, v79
	v_add_f32_e32 v81, v32, v33
	v_pk_mul_f32 v[32:33], v[8:9], v[68:69]
	v_lshlrev_b32_e32 v89, 16, v176
	v_add_f32_e32 v32, v101, v32
	v_add_f32_e32 v79, v32, v33
	v_pk_mul_f32 v[32:33], v[48:49], v[88:89]
	v_and_b32_e32 v87, 0xffff0000, v176
	v_add_f32_e32 v32, v102, v32
	v_add_f32_e32 v75, v32, v33
	v_pk_mul_f32 v[32:33], v[6:7], v[86:87]
	v_mov_b32_e32 v82, v77
	v_add_f32_e32 v32, v105, v32
	v_add_f32_e32 v32, v32, v33
	v_cvt_pk_bf16_f32 v90, v75, v32
	v_cvt_pk_bf16_f32 v91, v81, v79
	v_cvt_pk_bf16_f32 v92, v73, v80
	v_cvt_pk_bf16_f32 v93, v63, v74
	s_nop 0
	v_mov_b32_e32 v80, v87
	v_mov_b32_e32 v84, v89
	v_mov_b32_e32 v74, v69
	global_store_dwordx4 v[28:29], v[90:93], off
	s_nop 0
	s_waitcnt vmcnt(13)
	v_and_b32_e32 v81, 0xffff0000, v190
	v_pk_mul_f32 v[94:95], v[6:7], v[80:81]
	v_lshlrev_b32_e32 v83, 16, v191
	v_add_f32_e32 v94, v70, v94
	v_and_b32_e32 v71, 0xffff0000, v192
	v_mov_b32_e32 v70, v65
	v_lshlrev_b32_e32 v85, 16, v190
	v_and_b32_e32 v75, 0xffff0000, v191
	v_pk_mul_f32 v[30:31], v[34:35], v[82:83]
	v_pk_mul_f32 v[100:101], v[2:3], v[70:71]
	v_add_f32_e32 v30, v72, v30
	v_add_f32_e32 v72, v106, v100
	v_lshlrev_b32_e32 v73, 16, v193
	v_add_f32_e32 v90, v72, v101
	v_mov_b32_e32 v72, v61
	v_pk_mul_f32 v[96:97], v[48:49], v[84:85]
	v_pk_mul_f32 v[98:99], v[8:9], v[74:75]
	v_pk_mul_f32 v[28:29], v[54:55], v[72:73]
	v_add_f32_e32 v43, v43, v96
	v_add_f32_e32 v96, v78, v98
	v_lshlrev_b32_e32 v79, 16, v192
	v_mov_b32_e32 v78, v67
	v_and_b32_e32 v63, 0xffff0000, v193
	v_add_f32_e32 v28, v62, v28
	v_mov_b32_e32 v62, v59
	v_pk_mul_f32 v[102:103], v[36:37], v[78:79]
	v_add_f32_e32 v91, v28, v29
	v_pk_mul_f32 v[28:29], v[4:5], v[62:63]
	v_add_f32_e32 v32, v104, v102
	v_add_f32_e32 v30, v30, v31
	v_add_f32_e32 v31, v96, v99
	v_add_f32_e32 v28, v107, v28
	v_add_f32_e32 v33, v43, v97
	v_add_f32_e32 v43, v94, v95
	v_add_f32_e32 v32, v32, v103
	v_add_f32_e32 v92, v28, v29
	v_cvt_pk_bf16_f32 v28, v33, v43
	v_cvt_pk_bf16_f32 v29, v30, v31
	v_cvt_pk_bf16_f32 v30, v32, v90
	v_cvt_pk_bf16_f32 v31, v91, v92
	global_store_dwordx4 v[26:27], v[28:31], off
	s_and_saveexec_b64 s[2:3], vcc
	s_cbranch_execz .LBB0_281
	s_load_dwordx2 s[16:17], s[0:1], 0xe0
	v_lshlrev_b64 v[30:31], 13, v[44:45]
	v_mov_b32_e32 v26, v85
	v_mov_b32_e32 v27, v81
	v_mov_b32_e32 v28, v83
	s_waitcnt lgkmcnt(0)
	v_lshl_add_u64 v[30:31], s[16:17], 0, v[30:31]
	v_lshl_add_u64 v[30:31], v[30:31], 0, v[0:1]
	v_lshl_add_u64 v[32:33], v[30:31], 0, s[34:35]
	v_add_co_u32_e32 v30, vcc, 0x9448000, v30
	v_mov_b32_e32 v29, v75
	s_nop 0
	v_addc_co_u32_e32 v31, vcc, 0, v31, vcc
	global_store_dwordx4 v[30:31], v[26:29], off
	s_nop 1
	v_mov_b32_e32 v26, v79
	v_mov_b32_e32 v27, v71
	v_mov_b32_e32 v28, v73
	v_mov_b32_e32 v29, v63
	global_store_dwordx4 v[32:33], v[26:29], off offset:16
